# grid.sync at the P0-P1 seam replaced by the XCD-hierarchical atomic barrier the other seams use
# baseline (speedup 1.0000x reference)
.LBB0_168:
	s_waitcnt vmcnt(0) lgkmcnt(0)
	s_barrier
	s_and_saveexec_b64 s[0:1], s[38:39]
	s_xor_b64 s[0:1], exec, s[0:1]
	s_cbranch_execz .Lgs0_238
	s_add_i32 s3, 0, 0x22020
	v_mov_b32_e32 v0, s3
	s_waitcnt vmcnt(0) expcnt(0) lgkmcnt(0)
	ds_read_b32 v2, v0
	s_add_i32 s3, 0, 0x22024
	v_mov_b32_e32 v0, s3
	ds_read_b32 v0, v0
	s_waitcnt lgkmcnt(1)
	v_cmp_ne_u32_e32 vcc, 0, v2
	s_cbranch_vccnz .Lgs0_201
	s_add_u32 s4, s66, 0x4200
	s_addc_u32 s5, s67, 0
	s_add_u32 s6, s66, 0x4400
	s_addc_u32 s7, s67, 0
	s_add_u32 s12, s66, 0x4500
	s_addc_u32 s13, s67, 0
	s_add_u32 s14, s66, 0x4600
	s_addc_u32 s15, s67, 0
	s_add_u32 s98, s66, 0x4700
	s_addc_u32 s99, s67, 0
	s_add_u32 s18, s66, 0x4800
	s_addc_u32 s19, s67, 0
	s_add_u32 s26, s66, 0x4900
	s_addc_u32 s27, s67, 0
	s_add_u32 s28, s66, 0x4a00
	s_addc_u32 s29, s67, 0
	s_add_u32 s30, s66, 0x4b00
	s_addc_u32 s31, s67, 0
	s_add_u32 s34, s66, 0x4c00
	s_addc_u32 s35, s67, 0
	s_add_u32 s36, s66, 0x4d00
	s_addc_u32 s37, s67, 0
	s_add_u32 s40, s66, 0x4e00
	s_addc_u32 s41, s67, 0
	s_add_u32 s48, s66, 0x4f00
	s_addc_u32 s49, s67, 0
	s_add_u32 s52, s66, 0x5000
	s_addc_u32 s53, s67, 0
	s_add_u32 s54, s66, 0x5100
	s_addc_u32 s55, s67, 0
	s_add_u32 s58, s66, 0x5200
	v_readlane_b32 s3, v252, 0
	s_addc_u32 s59, s67, 0
	s_mul_i32 s3, s65, s3
	s_add_u32 s60, s66, 0x5300
	s_mul_i32 s3, s3, s64
	s_addc_u32 s61, s67, 0
	s_mov_b32 s21, 1
	v_mov_b32_e32 v16, 0
	s_branch .Lgs0_189

.Lgs0_189:
	global_load_dword v15, v16, s[6:7] sc1
	s_waitcnt lgkmcnt(0)
	global_load_dword v0, v16, s[12:13] sc1
	global_load_dword v1, v16, s[14:15] sc1
	global_load_dword v2, v16, s[98:99] sc1
	global_load_dword v3, v16, s[18:19] sc1
	global_load_dword v4, v16, s[26:27] sc1
	global_load_dword v5, v16, s[28:29] sc1
	global_load_dword v6, v16, s[30:31] sc1
	global_load_dword v7, v16, s[34:35] sc1
	global_load_dword v8, v16, s[36:37] sc1
	global_load_dword v9, v16, s[40:41] sc1
	global_load_dword v10, v16, s[48:49] sc1
	global_load_dword v11, v16, s[52:53] sc1
	global_load_dword v12, v16, s[54:55] sc1
	global_load_dword v13, v16, s[58:59] sc1
	global_load_dword v14, v16, s[60:61] sc1
	s_mov_b64 s[70:71], -1
	s_mov_b64 s[72:73], -1
	s_waitcnt vmcnt(14)
	v_add_u32_e32 v17, v0, v15
	s_waitcnt vmcnt(13)
	v_add_u32_e32 v17, v17, v1
	s_waitcnt vmcnt(12)
	v_add_u32_e32 v17, v17, v2
	s_waitcnt vmcnt(11)
	v_add_u32_e32 v17, v17, v3
	s_waitcnt vmcnt(10)
	v_add_u32_e32 v17, v17, v4
	s_waitcnt vmcnt(9)
	v_add_u32_e32 v17, v17, v5
	s_waitcnt vmcnt(8)
	v_add_u32_e32 v17, v17, v6
	s_waitcnt vmcnt(7)
	v_add_u32_e32 v17, v17, v7
	s_waitcnt vmcnt(6)
	v_add_u32_e32 v17, v17, v8
	s_waitcnt vmcnt(5)
	v_add_u32_e32 v17, v17, v9
	s_waitcnt vmcnt(4)
	v_add_u32_e32 v17, v17, v10
	s_waitcnt vmcnt(3)
	v_add_u32_e32 v17, v17, v11
	s_waitcnt vmcnt(2)
	v_add_u32_e32 v17, v17, v12
	s_waitcnt vmcnt(1)
	v_add_u32_e32 v17, v17, v13
	s_waitcnt vmcnt(0)
	v_add_u32_e32 v17, v17, v14
	v_cmp_eq_u32_e32 vcc, s3, v17
	s_cbranch_vccnz .Lgs0_188
	s_and_b32 s25, s21, 0xff
	s_cmp_eq_u32 s25, 0
	s_mov_b64 s[74:75], -1
	s_sleep 1
	s_cbranch_scc1 .Lgs0_193
	s_and_b64 vcc, exec, s[74:75]
	s_cbranch_vccz .Lgs0_188

.Lgs0_203:
	s_or_b64 exec, exec, s[12:13]
	v_cvt_f32_u32_e32 v4, v2
	s_waitcnt vmcnt(0)
	v_readfirstlane_b32 s3, v3
	v_sub_u32_e32 v3, 0, v2
	v_rcp_iflag_f32_e32 v4, v4
	v_add_u32_e32 v5, s3, v1
	v_mul_f32_e32 v4, 0x4f7ffffe, v4
	v_cvt_u32_f32_e32 v4, v4
	v_mul_lo_u32 v1, v3, v4
	v_mul_hi_u32 v1, v4, v1
	v_add_u32_e32 v1, v4, v1
	v_mul_hi_u32 v1, v5, v1
	v_mul_lo_u32 v3, v1, v2
	v_sub_u32_e32 v3, v5, v3
	v_add_u32_e32 v4, 1, v1
	v_cmp_ge_u32_e32 vcc, v3, v2
	s_nop 1
	v_cndmask_b32_e32 v1, v1, v4, vcc
	v_sub_u32_e32 v4, v3, v2
	v_cndmask_b32_e32 v3, v3, v4, vcc
	v_add_u32_e32 v4, 1, v1
	v_cmp_ge_u32_e32 vcc, v3, v2
	v_add_u32_e32 v3, 1, v5
	s_nop 0
	v_cndmask_b32_e32 v1, v1, v4, vcc
	v_mul_lo_u32 v4, v2, v1
	v_add_u32_e32 v2, v4, v2
	v_cmp_ne_u32_e32 vcc, v3, v2
	s_and_saveexec_b64 s[6:7], vcc
	s_xor_b64 s[6:7], exec, s[6:7]
	s_cbranch_execz .Lgs0_217
	s_waitcnt lgkmcnt(0)
	v_mov_b32_e32 v0, 0x2000
	global_load_dword v0, v0, s[4:5] offset:1024 sc1
	s_add_u32 s98, s4, 0x2400
	s_addc_u32 s99, s5, 0
	s_waitcnt vmcnt(0)
	v_cmp_eq_u32_e32 vcc, v0, v1
	s_and_saveexec_b64 s[12:13], vcc
	s_cbranch_execz .Lgs0_216
	s_add_u32 s14, s66, 0x4200
	s_addc_u32 s15, s67, 0
	s_mov_b32 s3, 1
	s_mov_b64 s[18:19], 0
	v_mov_b32_e32 v0, 0
	s_branch .Lgs0_207

.Lgs0_209:
	global_load_dword v2, v0, s[98:99] sc1
	s_add_i32 s3, s3, 1
	s_mov_b64 s[30:31], -1
	s_waitcnt vmcnt(0)
	v_cmp_ne_u32_e32 vcc, v2, v1
	s_orn2_b64 s[28:29], vcc, exec
	s_branch .Lgs0_206

.Lgs0_213:
	s_or_b64 exec, exec, s[18:19]
	s_xor_b64 s[98:99], s[26:27], -1
	s_and_saveexec_b64 s[18:19], s[98:99]
	s_xor_b64 s[18:19], exec, s[18:19]
	s_cbranch_execz .Lgs0_216
	s_mov_b64 s[98:99], exec
	v_mbcnt_lo_u32_b32 v0, s98, 0
	v_mbcnt_hi_u32_b32 v0, s99, v0
	v_cmp_eq_u32_e32 vcc, 0, v0
	s_and_b64 s[18:19], exec, vcc
	s_mov_b64 exec, s[18:19]
	s_cbranch_execz .Lgs0_216
	s_bcnt1_i32_b64 s3, s[98:99]
	v_mov_b32_e32 v0, 0
	v_mov_b32_e32 v1, s3
	global_atomic_add v0, v1, s[14:15]

.Lgs0_220:
	s_or_b64 exec, exec, s[14:15]
	v_cvt_f32_u32_e32 v3, v0
	s_waitcnt vmcnt(0)
	v_readfirstlane_b32 s3, v2
	s_add_u32 s14, s66, 0x7500
	s_addc_u32 s15, s67, 0
	v_rcp_iflag_f32_e32 v3, v3
	v_add_u32_e32 v1, s3, v1
	v_add_u32_e32 v4, 1, v1
	s_mov_b64 s[98:99], -1
	v_mul_f32_e32 v2, 0x4f7ffffe, v3
	v_cvt_u32_f32_e32 v2, v2
	v_sub_u32_e32 v3, 0, v0
	v_mul_lo_u32 v3, v3, v2
	v_mul_hi_u32 v3, v2, v3
	v_add_u32_e32 v2, v2, v3
	v_mul_hi_u32 v2, v1, v2
	v_mul_lo_u32 v3, v2, v0
	v_sub_u32_e32 v1, v1, v3
	v_add_u32_e32 v5, 1, v2
	v_cmp_ge_u32_e32 vcc, v1, v0
	v_sub_u32_e32 v3, v1, v0
	s_nop 0
	v_cndmask_b32_e32 v2, v2, v5, vcc
	v_cndmask_b32_e32 v1, v1, v3, vcc
	v_add_u32_e32 v3, 1, v2
	v_cmp_ge_u32_e32 vcc, v1, v0
	s_nop 1
	v_cndmask_b32_e32 v2, v2, v3, vcc
	v_mul_lo_u32 v1, v0, v2
	v_add_u32_e32 v0, v1, v0
	v_cmp_ne_u32_e32 vcc, v4, v0
	v_mov_b64_e32 v[0:1], s[14:15]
	s_and_saveexec_b64 s[12:13], vcc
	s_cbranch_execz .Lgs0_232
	v_mov_b32_e32 v0, 0
	global_load_dword v1, v0, s[14:15] sc1
	s_mov_b64 s[26:27], 0
	s_waitcnt vmcnt(0)
	v_cmp_eq_u32_e32 vcc, v1, v2
	s_and_saveexec_b64 s[18:19], vcc
	s_cbranch_execz .Lgs0_231
	s_add_u32 s98, s66, 0x4200
	s_addc_u32 s99, s67, 0
	s_mov_b32 s3, 1
	s_branch .Lgs0_224

.Lgs0_227:
	global_load_dword v1, v0, s[98:99] sc1
	s_waitcnt vmcnt(0)
	v_cmp_eq_u32_e32 vcc, 0, v1
	s_cbranch_vccnz .Lgs0_229
	s_mov_b64 s[30:31], -1
	s_mov_b64 s[36:37], -1
	s_branch .Lgs0_223

.Lgs0_231:
	s_or_b64 exec, exec, s[18:19]
	v_mov_b64_e32 v[0:1], s[98:99]
	s_orn2_b64 s[98:99], s[26:27], exec
.Lgs0_232:
	s_or_b64 exec, exec, s[12:13]
	s_and_saveexec_b64 s[12:13], s[98:99]
	s_cbranch_execz .Lgs0_234
	v_mov_b32_e32 v2, 1
	global_atomic_add v[0:1], v2, off

.Lgs0_238:
	s_or_b64 exec, exec, s[0:1]
	s_add_u32 s86, s66, 0x200000
	s_addc_u32 s87, s67, 0
	s_lshl_b32 s0, s2, 8
	s_lshl_b32 s1, s90, 5
	s_add_i32 s20, s1, s0
	s_cmp_lt_i32 s20, 0x10000
	s_cselect_b64 s[10:11], -1, 0
	s_lshl_b32 s24, s64, 8
	v_mov_b32_e32 v0, v210
	s_and_b64 vcc, exec, s[10:11]
	v_mbcnt_lo_u32_b32 v208, -1, 0
	s_waitcnt lgkmcnt(0)
	s_barrier
	s_cbranch_vccz .LBB0_185
	v_lshlrev_b32_e32 v1, 2, v0
	v_and_b32_e32 v2, 0xfc, v1
	v_mbcnt_hi_u32_b32 v1, -1, v208
	v_and_b32_e32 v3, 64, v1
	v_add_u32_e32 v3, 64, v3
	v_xor_b32_e32 v6, 1, v1
	v_cmp_lt_i32_e32 vcc, v6, v3
	s_ashr_i32 s21, s20, 31
	s_lshl_b64 s[0:1], s[20:21], 11
	v_cndmask_b32_e32 v6, v1, v6, vcc
	v_lshlrev_b32_e32 v72, 2, v6
	v_xor_b32_e32 v6, 2, v1
	v_cmp_lt_i32_e32 vcc, v6, v3
	v_mov_b32_e32 v5, 0
	v_lshlrev_b32_e32 v4, 2, v2
	v_cndmask_b32_e32 v6, v1, v6, vcc
	v_lshlrev_b32_e32 v73, 2, v6
	v_xor_b32_e32 v6, 4, v1
	v_cmp_lt_i32_e32 vcc, v6, v3
	v_and_b32_e32 v0, 63, v0
	s_add_u32 s0, s66, s0
	v_cndmask_b32_e32 v6, v1, v6, vcc
	v_lshlrev_b32_e32 v74, 2, v6
	v_xor_b32_e32 v6, 8, v1
	v_cmp_lt_i32_e32 vcc, v6, v3
	v_lshl_add_u64 v[48:49], s[8:9], 0, v[4:5]
	v_lshl_add_u64 v[50:51], s[16:17], 0, v[4:5]
	v_cndmask_b32_e32 v6, v1, v6, vcc
	v_lshlrev_b32_e32 v75, 2, v6
	v_xor_b32_e32 v6, 16, v1
	v_cmp_lt_i32_e32 vcc, v6, v3
	v_lshlrev_b32_e32 v4, 3, v0
	s_addc_u32 s1, s67, s1
	v_cndmask_b32_e32 v6, v1, v6, vcc
	v_lshlrev_b32_e32 v76, 2, v6
	v_xor_b32_e32 v6, 32, v1
	v_cmp_lt_i32_e32 vcc, v6, v3
	v_or_b32_e32 v8, 0x200, v2
	v_or_b32_e32 v10, 0x300, v2
	v_cndmask_b32_e32 v1, v1, v6, vcc
	v_lshlrev_b32_e32 v77, 2, v1
	v_or_b32_e32 v6, 0x100, v2
	v_lshl_add_u64 v[0:1], s[0:1], 0, v[4:5]
	s_mov_b64 s[0:1], 0x4000400
	s_ashr_i32 s25, s24, 31
	v_lshl_add_u64 v[52:53], v[0:1], 0, s[0:1]
	s_lshl_b64 s[4:5], s[24:25], 11
	v_lshlrev_b32_e32 v78, 2, v2
	v_lshlrev_b32_e32 v79, 2, v6
	v_lshlrev_b32_e32 v80, 2, v8
	v_lshlrev_b32_e32 v81, 2, v10
	v_mov_b32_e32 v82, 0x358637bd
	s_mov_b32 s3, 0xf800000
	v_mov_b32_e32 v83, 0x260
	s_movk_i32 s18, 0x7fff
	s_mov_b32 s19, 0xffff0000
	s_mov_b64 s[6:7], 0x800
	s_mov_b32 s12, s20
	s_branch .LBB0_181

	.amdhsa_kernel _Z8fwd_mega4Args
		.amdhsa_group_segment_fixed_size 0
		.amdhsa_private_segment_fixed_size 0
		.amdhsa_kernarg_size 432
		.amdhsa_user_sgpr_count 2
		.amdhsa_user_sgpr_dispatch_ptr 0
		.amdhsa_user_sgpr_queue_ptr 0
		.amdhsa_user_sgpr_kernarg_segment_ptr 1
		.amdhsa_user_sgpr_dispatch_id 0
		.amdhsa_user_sgpr_kernarg_preload_length 0
		.amdhsa_user_sgpr_kernarg_preload_offset 0
		.amdhsa_user_sgpr_private_segment_size 0
		.amdhsa_uses_dynamic_stack 0
		.amdhsa_enable_private_segment 0
		.amdhsa_system_sgpr_workgroup_id_x 1
		.amdhsa_system_sgpr_workgroup_id_y 0
		.amdhsa_system_sgpr_workgroup_id_z 0
		.amdhsa_system_sgpr_workgroup_info 0
		.amdhsa_system_vgpr_workitem_id 2
		.amdhsa_next_free_vgpr 253
		.amdhsa_next_free_sgpr 102
		.amdhsa_accum_offset 256
		.amdhsa_reserve_vcc 1
		.amdhsa_float_round_mode_32 0
		.amdhsa_float_round_mode_16_64 0
		.amdhsa_float_denorm_mode_32 3
		.amdhsa_float_denorm_mode_16_64 3
		.amdhsa_dx10_clamp 1
		.amdhsa_ieee_mode 1
		.amdhsa_fp16_overflow 0
		.amdhsa_tg_split 0
		.amdhsa_exception_fp_ieee_invalid_op 0
		.amdhsa_exception_fp_denorm_src 0
		.amdhsa_exception_fp_ieee_div_zero 0
		.amdhsa_exception_fp_ieee_overflow 0
		.amdhsa_exception_fp_ieee_underflow 0
		.amdhsa_exception_fp_ieee_inexact 0
		.amdhsa_exception_int_div_zero 0
	.end_amdhsa_kernel

.Lfunc_end0:
	.size	_Z8fwd_mega4Args, .Lfunc_end0-_Z8fwd_mega4Args
	.set _Z8fwd_mega4Args.num_vgpr, 253
	.set _Z8fwd_mega4Args.num_agpr, 0
	.set _Z8fwd_mega4Args.numbered_sgpr, 102
	.set _Z8fwd_mega4Args.num_named_barrier, 0
	.set _Z8fwd_mega4Args.private_seg_size, 0
	.set _Z8fwd_mega4Args.uses_vcc, 1
	.set _Z8fwd_mega4Args.uses_flat_scratch, 0
	.set _Z8fwd_mega4Args.has_dyn_sized_stack, 0
	.set _Z8fwd_mega4Args.has_recursion, 0
	.set _Z8fwd_mega4Args.has_indirect_call, 0

amdhsa.kernels:
  - .agpr_count:     0
    .args:
      - .offset:         0
        .size:           176
        .value_kind:     by_value
      - .offset:         176
        .size:           4
        .value_kind:     hidden_block_count_x
      - .offset:         180
        .size:           4
        .value_kind:     hidden_block_count_y
      - .offset:         184
        .size:           4
        .value_kind:     hidden_block_count_z
      - .offset:         188
        .size:           2
        .value_kind:     hidden_group_size_x
      - .offset:         190
        .size:           2
        .value_kind:     hidden_group_size_y
      - .offset:         192
        .size:           2
        .value_kind:     hidden_group_size_z
      - .offset:         194
        .size:           2
        .value_kind:     hidden_remainder_x
      - .offset:         196
        .size:           2
        .value_kind:     hidden_remainder_y
      - .offset:         198
        .size:           2
        .value_kind:     hidden_remainder_z
      - .offset:         216
        .size:           8
        .value_kind:     hidden_global_offset_x
      - .offset:         224
        .size:           8
        .value_kind:     hidden_global_offset_y
      - .offset:         232
        .size:           8
        .value_kind:     hidden_global_offset_z
      - .offset:         240
        .size:           2
        .value_kind:     hidden_grid_dims
      - .offset:         264
        .size:           8
        .value_kind:     hidden_multigrid_sync_arg
      - .offset:         296
        .size:           4
        .value_kind:     hidden_dynamic_lds_size
    .group_segment_fixed_size: 0
    .kernarg_segment_align: 8
    .kernarg_segment_size: 432
    .language:       OpenCL C
    .language_version:
      - 2
      - 0
    .max_flat_workgroup_size: 512
    .name:           _Z8fwd_mega4Args
    .private_segment_fixed_size: 0
    .sgpr_count:     108
    .sgpr_spill_count: 10
    .symbol:         _Z8fwd_mega4Args.kd
    .uniform_work_group_size: 1
    .uses_dynamic_stack: false
    .vgpr_count:     253
    .vgpr_spill_count: 0
    .wavefront_size: 64
